# strategy: stagger in the dilated-attention step loop (waves 4-7 stage the next tile at the top of the step, waves 0-3 at the end)
# speedup vs baseline: 1.0078x; 1.0033x over previous
; __device__ __forceinline__ void c_phase(const bf16_t* Z, bf16_t* MIX, float* LSE, ldsp lds, int pi, int bx, int G, unsigned& gt, int wave0, int ucount) {
;     ...
;         for (int kt = kt0; kt <= kt1; ++kt) {
;             const ldsp buf = lds + (gt & 1u) * 32768, nxt = lds + ((gt + 1u) & 1u) * 32768;
;             if (kt == kt1 - 1) {
;                 if (pi > 0) { lse_old = *lsep;
; #pragma unroll
;                     for (int i = 0; i < 4; ++i) orun[i] = ldg16(orow + i * ostep); }
;             }
;             if (64 * kt <= q0 + 31 && 64 * kt + 63 >= q0 - 128) {
;                 attn_step(buf + hsel * 16384, buf + hsel * 16384 + 8192, qr, o, m, negm, l, ql - 128 - 64 * kt, ql - 64 * kt, true, !started, wsf, lane, r32, hi); started = true; }
;             if (kt < kt1 || has_next) { tile_store(nxt, rka, rva, key, ch); tile_store(nxt + 16384, rkb, rvb, key, ch); }
.Lc_pre_join:
.LBB0_1036:
	s_cmp_eq_u32 s87, s84
	s_cselect_b64 s[90:91], -1, 0
	v_readlane_b32 s100, v254, 16
	s_nop 1
	s_cmp_eq_u32 s100, 1
	s_cbranch_scc0 .Lc_stg_top_skip
	s_and_b32 s79, s77, 0x8000
	s_cmp_gt_i32 s84, s87
	s_cselect_b64 s[8:9], -1, 0
	s_xor_b64 s[10:11], s[40:41], -1
	s_and_b64 s[8:9], s[10:11], s[8:9]
	s_and_b64 vcc, exec, s[8:9]
	s_cbranch_vccnz .Lc_stg_64
	s_xor_b32 s8, s79, 0x8000
	s_add_i32 s8, s8, 0
	v_add3_u32 v64, s8, v202, v203
	v_add3_u32 v65, s8, v204, v205
	v_add3_u32 v65, v65, v206, v207
	s_waitcnt vmcnt(3)
	ds_write_b128 v64, v[128:131]
	s_waitcnt vmcnt(2)
	ds_write_b128 v65, v[132:135] offset:8192
	s_waitcnt vmcnt(1)
	ds_write_b128 v64, v[136:139] offset:16384
	s_waitcnt vmcnt(0)
	ds_write_b128 v65, v[140:143] offset:24576

; __device__ __forceinline__ void c_phase(const bf16_t* Z, bf16_t* MIX, float* LSE, ldsp lds, int pi, int bx, int G, unsigned& gt, int wave0, int ucount) {
;     ...
;             if (kt == kt1 - 1) {
;                 if (pi > 0) { lse_old = *lsep;
; #pragma unroll
;                     for (int i = 0; i < 4; ++i) orun[i] = ldg16(orow + i * ostep); }
;             }
.Lc_stg_top_skip:
	s_and_b64 s[8:9], s[82:83], s[90:91]
	s_andn2_b64 vcc, exec, s[8:9]
	s_cbranch_vccnz .LBB0_1038
	global_load_dword v191, v[194:195], off
	global_load_dwordx4 v[156:159], v[192:193], off
	global_load_dwordx4 v[152:155], v[196:197], off
	global_load_dwordx4 v[148:151], v[198:199], off
	global_load_dwordx4 v[144:147], v[200:201], off

; #define C_LOADP(p_) do { const bf16_t* q_ = (p_); rka = ldg16(q_ + kvlane); rva = ldg16(q_ + (size_t)16 * T * 64 + kvlane); rkb = ldg16(q_ + (size_t)T * 64 + kvlane); rvb = ldg16(q_ + (size_t)17 * T * 64 + kvlane); } while (0)
; __device__ __forceinline__ void c_phase(const bf16_t* Z, bf16_t* MIX, float* LSE, ldsp lds, int pi, int bx, int G, unsigned& gt, int wave0, int ucount) {
;     ...
;             if (kt < kt1 || has_next) { tile_store(nxt, rka, rva, key, ch); tile_store(nxt + 16384, rkb, rvb, key, ch); }
;             if (kt + 2 <= kt1) C_LOADP(kvp + (kt + 2) * tstride);
;             else if (has_next) { if (kt == kt1 - 1) C_LOADP(kvpn); else C_LOADP(kvpn + tstride); }
;             __syncthreads(); ++gt;
.LBB0_1062:
	v_readlane_b32 s100, v254, 16
	s_nop 1
	s_cmp_eq_u32 s100, 1
	s_cbranch_scc1 .LBB0_1071
	s_cmp_gt_i32 s84, s87
	s_cselect_b64 s[8:9], -1, 0
	s_xor_b64 s[10:11], s[40:41], -1
	s_and_b64 s[8:9], s[10:11], s[8:9]
	s_and_b64 vcc, exec, s[8:9]
	s_cbranch_vccnz .LBB0_1064
	s_xor_b32 s8, s79, 0x8000
	s_add_i32 s8, s8, 0
	v_add3_u32 v64, s8, v202, v203
	v_add3_u32 v65, s8, v204, v205
	v_add3_u32 v65, v65, v206, v207
	s_waitcnt vmcnt(3)
	ds_write_b128 v64, v[128:131]
	s_waitcnt vmcnt(2)
	ds_write_b128 v65, v[132:135] offset:8192
	s_waitcnt vmcnt(1)
	ds_write_b128 v64, v[136:139] offset:16384
	s_waitcnt vmcnt(0)
	ds_write_b128 v65, v[140:143] offset:24576
